# final output norm loop: software prefetch of next two rows into spare VGPR bank v86-117, staged vmcnt ladder removed, back-edge vmcnt(8); on top of P0 norm prefetch
# speedup vs baseline: 1.0052x; 1.0002x over previous
; template <bool HB, bool FINAL>
; __device__ __forceinline__ void norm_rows(const void* src, const bf16* y, float ys, bf16* hdst, const float* gain, bf16* xn, float* fout, float* fstage, int gw, int NGW, int lane) {
;     ...
;     for (int m0 = gw; m0 < T; m0 += 2 * NGW) {
;         f32x4 v[2][4]; u32x2 yw[2][4];
; #pragma unroll
;         for (int r = 0; r < 2; ++r) { const int m = m0 + r * NGW;
;             if (HB) { const u32x2* hr = (const u32x2*)((const bf16*)src + (size_t)m * D) + lane;
; #pragma unroll
;                 for (int j = 0; j < 4; ++j) { const u32x2 w = hr[64 * j]; v[r][j] = (f32x4){__uint_as_float(w.x << 16), __uint_as_float(w.x & 0xffff0000u), __uint_as_float(w.y << 16), __uint_as_float(w.y & 0xffff0000u)}; }
;             } else { const f32x4* xr = (const f32x4*)((const float*)src + (size_t)m * D) + lane;
; #pragma unroll
;                 for (int j = 0; j < 4; ++j) v[r][j] = xr[64 * j]; }
;             if (y) { const u32x2* yr = (const u32x2*)(y + (size_t)m * D) + lane;
; #pragma unroll
;                 for (int j = 0; j < 4; ++j) yw[r][j] = yr[64 * j]; } }
;         float s[2];
; #pragma unroll
;         for (int r = 0; r < 2; ++r) { s[r] = 0.f;
;             if (y) {
; #pragma unroll
;                 for (int j = 0; j < 4; ++j) { const u32x2 w = yw[r][j];
;                     v[r][j].x += ys * __uint_as_float(w.x << 16); v[r][j].y += ys * __uint_as_float(w.x & 0xffff0000u); v[r][j].z += ys * __uint_as_float(w.y << 16); v[r][j].w += ys * __uint_as_float(w.y & 0xffff0000u); } }
; #pragma unroll
;             for (int j = 0; j < 4; ++j) s[r] += (v[r][j].x * v[r][j].x + v[r][j].y * v[r][j].y) + (v[r][j].z * v[r][j].z + v[r][j].w * v[r][j].w); }
.LBB0_272:
	s_ashr_i32 s7, s6, 31
	s_lshl_b64 s[8:9], s[6:7], 11
	v_lshl_add_u64 v[118:119], v[18:19], 0, s[8:9]
	global_load_dwordx2 v[86:87], v[118:119], off
	global_load_dwordx2 v[88:89], v[118:119], off offset:512
	global_load_dwordx2 v[90:91], v[118:119], off offset:1024
	global_load_dwordx2 v[92:93], v[118:119], off offset:1536
	v_lshl_add_u64 v[118:119], v[20:21], 0, s[8:9]
	global_load_dwordx2 v[94:95], v[118:119], off
	global_load_dwordx2 v[96:97], v[118:119], off offset:512
	global_load_dwordx2 v[98:99], v[118:119], off offset:1024
	global_load_dwordx2 v[100:101], v[118:119], off offset:1536
	s_add_i32 s8, s6, s33
	s_ashr_i32 s9, s8, 31
	s_lshl_b64 s[10:11], s[8:9], 11
	v_lshl_add_u64 v[118:119], v[18:19], 0, s[10:11]
	global_load_dwordx2 v[102:103], v[118:119], off
	global_load_dwordx2 v[104:105], v[118:119], off offset:512
	global_load_dwordx2 v[106:107], v[118:119], off offset:1024
	global_load_dwordx2 v[108:109], v[118:119], off offset:1536
	v_lshl_add_u64 v[118:119], v[20:21], 0, s[10:11]
	global_load_dwordx2 v[110:111], v[118:119], off
	global_load_dwordx2 v[112:113], v[118:119], off offset:512
	global_load_dwordx2 v[114:115], v[118:119], off offset:1024
	global_load_dwordx2 v[116:117], v[118:119], off offset:1536
	s_waitcnt vmcnt(0)
.LF_copy:
	s_ashr_i32 s7, s6, 31
	s_add_i32 s8, s6, s33
	s_ashr_i32 s9, s8, 31
	v_mov_b32_e32 v26, v86
	v_mov_b32_e32 v27, v87
	v_mov_b32_e32 v30, v88
	v_mov_b32_e32 v31, v89
	v_mov_b32_e32 v34, v90
	v_mov_b32_e32 v35, v91
	v_mov_b32_e32 v40, v92
	v_mov_b32_e32 v41, v93
	v_mov_b32_e32 v28, v94
	v_mov_b32_e32 v29, v95
	v_mov_b32_e32 v32, v96
	v_mov_b32_e32 v33, v97
	v_mov_b32_e32 v36, v98
	v_mov_b32_e32 v37, v99
	v_mov_b32_e32 v62, v100
	v_mov_b32_e32 v63, v101
	v_mov_b32_e32 v50, v102
	v_mov_b32_e32 v51, v103
	v_mov_b32_e32 v46, v104
	v_mov_b32_e32 v47, v105
	v_mov_b32_e32 v42, v106
	v_mov_b32_e32 v43, v107
	v_mov_b32_e32 v38, v108
	v_mov_b32_e32 v39, v109
	v_mov_b32_e32 v54, v110
	v_mov_b32_e32 v55, v111
	v_mov_b32_e32 v52, v112
	v_mov_b32_e32 v53, v113
	v_mov_b32_e32 v48, v114
	v_mov_b32_e32 v49, v115
	v_mov_b32_e32 v44, v116
	v_mov_b32_e32 v45, v117
	s_add_i32 s22, s8, s33
	s_cmpk_gt_i32 s22, 0x7fff
	s_cbranch_scc1 .LF_C
	s_ashr_i32 s23, s22, 31
	s_lshl_b64 s[18:19], s[22:23], 11
	v_lshl_add_u64 v[118:119], v[18:19], 0, s[18:19]
	global_load_dwordx2 v[86:87], v[118:119], off
	global_load_dwordx2 v[88:89], v[118:119], off offset:512
	global_load_dwordx2 v[90:91], v[118:119], off offset:1024
	global_load_dwordx2 v[92:93], v[118:119], off offset:1536
	v_lshl_add_u64 v[118:119], v[20:21], 0, s[18:19]
	global_load_dwordx2 v[94:95], v[118:119], off
	global_load_dwordx2 v[96:97], v[118:119], off offset:512
	global_load_dwordx2 v[98:99], v[118:119], off offset:1024
	global_load_dwordx2 v[100:101], v[118:119], off offset:1536
	s_add_i32 s22, s22, s33
	s_ashr_i32 s23, s22, 31
	s_lshl_b64 s[18:19], s[22:23], 11
	v_lshl_add_u64 v[118:119], v[18:19], 0, s[18:19]
	global_load_dwordx2 v[102:103], v[118:119], off
	global_load_dwordx2 v[104:105], v[118:119], off offset:512
	global_load_dwordx2 v[106:107], v[118:119], off offset:1024
	global_load_dwordx2 v[108:109], v[118:119], off offset:1536
	v_lshl_add_u64 v[118:119], v[20:21], 0, s[18:19]
	global_load_dwordx2 v[110:111], v[118:119], off
	global_load_dwordx2 v[112:113], v[118:119], off offset:512
	global_load_dwordx2 v[114:115], v[118:119], off offset:1024
	global_load_dwordx2 v[116:117], v[118:119], off offset:1536
.LF_C:
	s_lshl_b64 s[6:7], s[6:7], 12
	v_lshlrev_b32_e32 v24, 16, v26
	v_and_b32_e32 v25, 0xffff0000, v26
	v_lshlrev_b32_e32 v64, 16, v28
	v_and_b32_e32 v65, 0xffff0000, v28
	v_lshlrev_b32_e32 v26, 16, v27
	v_and_b32_e32 v27, 0xffff0000, v27
	v_lshlrev_b32_e32 v28, 16, v29
	v_and_b32_e32 v29, 0xffff0000, v29
	v_pk_fma_f32 v[24:25], v[64:65], 0.5, v[24:25] op_sel_hi:[1,0,1]
	v_pk_fma_f32 v[26:27], v[28:29], 0.5, v[26:27] op_sel_hi:[1,0,1]
	v_lshlrev_b32_e32 v28, 16, v30
	v_and_b32_e32 v29, 0xffff0000, v30
	v_lshlrev_b32_e32 v64, 16, v32
	v_and_b32_e32 v65, 0xffff0000, v32
	v_lshlrev_b32_e32 v30, 16, v31
	v_and_b32_e32 v31, 0xffff0000, v31
	v_lshlrev_b32_e32 v32, 16, v33
	v_and_b32_e32 v33, 0xffff0000, v33
	v_pk_fma_f32 v[28:29], v[64:65], 0.5, v[28:29] op_sel_hi:[1,0,1]
	v_pk_fma_f32 v[30:31], v[32:33], 0.5, v[30:31] op_sel_hi:[1,0,1]
	v_lshlrev_b32_e32 v32, 16, v34
	v_and_b32_e32 v33, 0xffff0000, v34
	v_lshlrev_b32_e32 v64, 16, v36
	v_and_b32_e32 v65, 0xffff0000, v36
	v_lshlrev_b32_e32 v34, 16, v35
	v_and_b32_e32 v35, 0xffff0000, v35
	v_lshlrev_b32_e32 v36, 16, v37
	v_and_b32_e32 v37, 0xffff0000, v37
	v_pk_fma_f32 v[32:33], v[64:65], 0.5, v[32:33] op_sel_hi:[1,0,1]
	v_pk_fma_f32 v[34:35], v[36:37], 0.5, v[34:35] op_sel_hi:[1,0,1]
	v_lshlrev_b32_e32 v36, 16, v40
	v_and_b32_e32 v37, 0xffff0000, v40
	v_lshlrev_b32_e32 v64, 16, v62
	v_and_b32_e32 v65, 0xffff0000, v62
	v_pk_fma_f32 v[36:37], v[64:65], 0.5, v[36:37] op_sel_hi:[1,0,1]
	v_lshlrev_b32_e32 v40, 16, v41
	v_and_b32_e32 v41, 0xffff0000, v41
	v_lshlrev_b32_e32 v62, 16, v63
	v_and_b32_e32 v63, 0xffff0000, v63
	v_mov_b32_e32 v64, v25
	v_mov_b32_e32 v65, v27
	v_pk_fma_f32 v[40:41], v[62:63], 0.5, v[40:41] op_sel_hi:[1,0,1]
	v_mov_b32_e32 v62, v24
	v_mov_b32_e32 v63, v26
	v_pk_mul_f32 v[64:65], v[64:65], v[64:65]
	v_mov_b32_e32 v66, v29
	v_mov_b32_e32 v67, v31
	v_pk_fma_f32 v[62:63], v[62:63], v[62:63], v[64:65]
	v_mov_b32_e32 v64, v28
	v_mov_b32_e32 v65, v30
	v_pk_mul_f32 v[66:67], v[66:67], v[66:67]
	v_mul_f32_e32 v0, v33, v33
	v_pk_fma_f32 v[64:65], v[64:65], v[64:65], v[66:67]
	v_pk_fma_f32 v[66:67], v[32:33], v[32:33], v[0:1] op_sel_hi:[1,1,0]
	v_mul_f32_e32 v0, v35, v35
; __device__ __forceinline__ unsigned cvt_pk_bf16(float lo, float hi) { f32x2_t v = {lo, hi}; bf16x2_t b = __builtin_convertvector(v, bf16x2_t); return __builtin_bit_cast(unsigned, b); }
; template <bool HB, bool FINAL>
; __device__ __forceinline__ void norm_rows(const void* src, const bf16* y, float ys, bf16* hdst, const float* gain, bf16* xn, float* fout, float* fstage, int gw, int NGW, int lane) {
;     ...
;         for (int r = 0; r < 2; ++r) { s[r] = 0.f;
;             if (y) {
; #pragma unroll
;                 for (int j = 0; j < 4; ++j) { const u32x2 w = yw[r][j];
;                     v[r][j].x += ys * __uint_as_float(w.x << 16); v[r][j].y += ys * __uint_as_float(w.x & 0xffff0000u); v[r][j].z += ys * __uint_as_float(w.y << 16); v[r][j].w += ys * __uint_as_float(w.y & 0xffff0000u); } }
; #pragma unroll
;             for (int j = 0; j < 4; ++j) s[r] += (v[r][j].x * v[r][j].x + v[r][j].y * v[r][j].y) + (v[r][j].z * v[r][j].z + v[r][j].w * v[r][j].w); }
; #pragma unroll
;         for (int o = 1; o < 64; o <<= 1) { s[0] += __shfl_xor(s[0], o); s[1] += __shfl_xor(s[1], o); }
; #pragma unroll
;         for (int r = 0; r < 2; ++r) { const int m = m0 + r * NGW; const float rstd = rsqrtf(s[r] * (1.f / D) + EPS);
;             if (!FINAL && hdst) { u32x2* hr = (u32x2*)(hdst + (size_t)m * D) + lane;
; #pragma unroll
;                 for (int j = 0; j < 4; ++j) { u32x2 w; w.x = cvt_pk_bf16(v[r][j].x, v[r][j].y); w.y = cvt_pk_bf16(v[r][j].z, v[r][j].w); hr[64 * j] = w; } }
;             if (FINAL) { f32x4* o = (f32x4*)((m >= T / 2 ? fout : fstage) + (size_t)m * D) + lane;
; #pragma unroll
;                 for (int j = 0; j < 4; ++j) o[64 * j] = v[r][j] * rstd * gv[j];
	v_pk_add_f32 v[62:63], v[62:63], v[62:63] op_sel:[0,1] op_sel_hi:[1,0]
	v_pk_add_f32 v[64:65], v[64:65], v[64:65] op_sel:[0,1] op_sel_hi:[1,0]
	v_pk_fma_f32 v[68:69], v[34:35], v[34:35], v[0:1] op_sel_hi:[1,1,0]
	v_pk_mul_f32 v[70:71], v[36:37], v[36:37]
	v_pk_mul_f32 v[72:73], v[40:41], v[40:41]
	v_mov_b32_e32 v63, v70
	v_mov_b32_e32 v65, v71
	v_mov_b32_e32 v67, v72
	v_mov_b32_e32 v69, v73
	v_pk_add_f32 v[62:63], v[62:63], v[64:65]
	v_pk_add_f32 v[64:65], v[66:67], v[68:69]
	v_lshlrev_b32_e32 v66, 16, v54
	v_pk_add_f32 v[62:63], v[62:63], v[64:65]
	v_lshlrev_b32_e32 v64, 16, v50
	v_and_b32_e32 v65, 0xffff0000, v50
	v_and_b32_e32 v67, 0xffff0000, v54
	v_lshlrev_b32_e32 v50, 16, v51
	v_and_b32_e32 v51, 0xffff0000, v51
	v_lshlrev_b32_e32 v54, 16, v55
	v_and_b32_e32 v55, 0xffff0000, v55
	v_pk_fma_f32 v[64:65], v[66:67], 0.5, v[64:65] op_sel_hi:[1,0,1]
	v_pk_fma_f32 v[50:51], v[54:55], 0.5, v[50:51] op_sel_hi:[1,0,1]
	v_lshlrev_b32_e32 v54, 16, v46
	v_and_b32_e32 v55, 0xffff0000, v46
	v_lshlrev_b32_e32 v66, 16, v52
	v_and_b32_e32 v67, 0xffff0000, v52
	v_lshlrev_b32_e32 v46, 16, v47
	v_and_b32_e32 v47, 0xffff0000, v47
	v_lshlrev_b32_e32 v52, 16, v53
	v_and_b32_e32 v53, 0xffff0000, v53
	v_pk_fma_f32 v[54:55], v[66:67], 0.5, v[54:55] op_sel_hi:[1,0,1]
	v_pk_fma_f32 v[46:47], v[52:53], 0.5, v[46:47] op_sel_hi:[1,0,1]
	v_lshlrev_b32_e32 v52, 16, v42
	v_and_b32_e32 v53, 0xffff0000, v42
	v_lshlrev_b32_e32 v66, 16, v48
	v_and_b32_e32 v67, 0xffff0000, v48
	v_lshlrev_b32_e32 v42, 16, v43
	v_and_b32_e32 v43, 0xffff0000, v43
	v_lshlrev_b32_e32 v48, 16, v49
	v_and_b32_e32 v49, 0xffff0000, v49
	v_pk_fma_f32 v[52:53], v[66:67], 0.5, v[52:53] op_sel_hi:[1,0,1]
	v_pk_fma_f32 v[42:43], v[48:49], 0.5, v[42:43] op_sel_hi:[1,0,1]
	v_lshlrev_b32_e32 v48, 16, v38
	v_and_b32_e32 v49, 0xffff0000, v38
	v_lshlrev_b32_e32 v66, 16, v44
	v_and_b32_e32 v67, 0xffff0000, v44
	v_pk_fma_f32 v[48:49], v[66:67], 0.5, v[48:49] op_sel_hi:[1,0,1]
	v_lshlrev_b32_e32 v38, 16, v39
	v_and_b32_e32 v39, 0xffff0000, v39
	v_lshlrev_b32_e32 v44, 16, v45
	v_and_b32_e32 v45, 0xffff0000, v45
	v_mov_b32_e32 v66, v65
	v_mov_b32_e32 v67, v51
	v_pk_fma_f32 v[38:39], v[44:45], 0.5, v[38:39] op_sel_hi:[1,0,1]
	v_mov_b32_e32 v44, v64
	v_mov_b32_e32 v45, v50
	v_pk_mul_f32 v[66:67], v[66:67], v[66:67]
	v_mov_b32_e32 v68, v55
	v_mov_b32_e32 v69, v47
	v_pk_fma_f32 v[44:45], v[44:45], v[44:45], v[66:67]
	v_mov_b32_e32 v66, v54
	v_mov_b32_e32 v67, v46
	v_pk_mul_f32 v[68:69], v[68:69], v[68:69]
	v_mul_f32_e32 v0, v53, v53
	v_pk_fma_f32 v[66:67], v[66:67], v[66:67], v[68:69]
	v_pk_fma_f32 v[68:69], v[52:53], v[52:53], v[0:1] op_sel_hi:[1,1,0]
	v_mul_f32_e32 v0, v43, v43
	v_pk_add_f32 v[44:45], v[44:45], v[44:45] op_sel:[0,1] op_sel_hi:[1,0]
	v_pk_add_f32 v[66:67], v[66:67], v[66:67] op_sel:[0,1] op_sel_hi:[1,0]
	v_pk_fma_f32 v[70:71], v[42:43], v[42:43], v[0:1] op_sel_hi:[1,1,0]
	v_pk_mul_f32 v[72:73], v[48:49], v[48:49]
	v_pk_mul_f32 v[74:75], v[38:39], v[38:39]
	v_mov_b32_e32 v45, v72
	v_mov_b32_e32 v67, v73
	v_mov_b32_e32 v69, v74
	v_mov_b32_e32 v71, v75
	v_pk_add_f32 v[44:45], v[44:45], v[66:67]
	v_pk_add_f32 v[66:67], v[68:69], v[70:71]
	v_mov_b32_e32 v69, v62
	v_pk_add_f32 v[44:45], v[44:45], v[66:67]
	v_lshl_add_u64 v[66:67], v[22:23], 0, s[6:7]
	v_mov_b32_e32 v68, v44
	v_mov_b32_e32 v62, v45
	v_pk_add_f32 v[44:45], v[68:69], v[62:63]
	ds_bpermute_b32 v63, v56, v45
	ds_bpermute_b32 v62, v56, v44
	s_mov_b32 s6, 0x3a800000
	s_waitcnt lgkmcnt(0)
	v_pk_add_f32 v[44:45], v[44:45], v[62:63]
	ds_bpermute_b32 v63, v57, v45
	ds_bpermute_b32 v62, v57, v44
	s_waitcnt lgkmcnt(0)
	v_pk_add_f32 v[44:45], v[44:45], v[62:63]
	ds_bpermute_b32 v63, v58, v45
	ds_bpermute_b32 v62, v58, v44
	s_waitcnt lgkmcnt(0)
	v_pk_add_f32 v[44:45], v[44:45], v[62:63]
	ds_bpermute_b32 v63, v59, v45
	ds_bpermute_b32 v62, v59, v44
	s_waitcnt lgkmcnt(0)
	v_pk_add_f32 v[44:45], v[44:45], v[62:63]
	ds_bpermute_b32 v63, v60, v45
	ds_bpermute_b32 v62, v60, v44
	s_waitcnt lgkmcnt(0)
	v_pk_add_f32 v[44:45], v[44:45], v[62:63]
	ds_bpermute_b32 v63, v61, v45
	ds_bpermute_b32 v62, v61, v44
	s_waitcnt lgkmcnt(0)
	v_pk_add_f32 v[44:45], v[44:45], v[62:63]
	s_nop 0
	v_pk_fma_f32 v[44:45], v[44:45], s[6:7], v[142:143] op_sel_hi:[1,0,0]
	s_nop 0
	v_mul_f32_e32 v0, 0x4b800000, v45
	v_cmp_gt_f32_e64 s[6:7], s72, v45
	v_cmp_gt_f32_e32 vcc, s72, v44
	s_nop 0
	v_cndmask_b32_e64 v0, v45, v0, s[6:7]
	v_rsq_f32_e32 v0, v0
	s_nop 0
	v_mul_f32_e32 v45, 0x45800000, v0
	v_cndmask_b32_e64 v0, v0, v45, s[6:7]
	v_pk_mul_f32 v[24:25], v[24:25], v[0:1] op_sel_hi:[1,0]
	v_pk_mul_f32 v[26:27], v[26:27], v[0:1] op_sel_hi:[1,0]
	v_pk_mul_f32 v[24:25], v[2:3], v[24:25]
	v_pk_mul_f32 v[26:27], v[4:5], v[26:27]
	global_store_dwordx4 v[66:67], v[24:27], off
	s_lshl_b64 s[6:7], s[8:9], 12
	s_nop 0
	v_pk_mul_f32 v[24:25], v[28:29], v[0:1] op_sel_hi:[1,0]
	v_pk_mul_f32 v[26:27], v[30:31], v[0:1] op_sel_hi:[1,0]
	v_pk_mul_f32 v[24:25], v[6:7], v[24:25]
	v_pk_mul_f32 v[26:27], v[8:9], v[26:27]
	global_store_dwordx4 v[66:67], v[24:27], off offset:1024
	v_lshl_add_u64 v[28:29], v[22:23], 0, s[6:7]
	s_add_i32 s6, s8, s33
	v_pk_mul_f32 v[24:25], v[32:33], v[0:1] op_sel_hi:[1,0]
	v_pk_mul_f32 v[26:27], v[34:35], v[0:1] op_sel_hi:[1,0]
	v_pk_mul_f32 v[24:25], v[10:11], v[24:25]
	v_pk_mul_f32 v[26:27], v[12:13], v[26:27]
	global_store_dwordx4 v[66:67], v[24:27], off offset:2048
	s_cmpk_gt_i32 s6, 0x7fff
	s_nop 0
	v_pk_mul_f32 v[24:25], v[36:37], v[0:1] op_sel_hi:[1,0]
	v_pk_mul_f32 v[26:27], v[40:41], v[0:1] op_sel_hi:[1,0]
	v_mul_f32_e32 v0, 0x4b800000, v44
	v_cndmask_b32_e32 v0, v44, v0, vcc
	v_rsq_f32_e32 v0, v0
	v_pk_mul_f32 v[26:27], v[16:17], v[26:27]
	v_pk_mul_f32 v[24:25], v[14:15], v[24:25]
	global_store_dwordx4 v[66:67], v[24:27], off offset:3072
	s_nop 1
	v_mul_f32_e32 v24, 0x45800000, v0
	v_cndmask_b32_e32 v0, v0, v24, vcc
	v_pk_mul_f32 v[24:25], v[64:65], v[0:1] op_sel_hi:[1,0]
	v_pk_mul_f32 v[26:27], v[50:51], v[0:1] op_sel_hi:[1,0]
	v_pk_mul_f32 v[24:25], v[2:3], v[24:25]
	v_pk_mul_f32 v[26:27], v[4:5], v[26:27]
	global_store_dwordx4 v[28:29], v[24:27], off
	s_nop 1
	v_pk_mul_f32 v[24:25], v[54:55], v[0:1] op_sel_hi:[1,0]
	v_pk_mul_f32 v[26:27], v[46:47], v[0:1] op_sel_hi:[1,0]
	v_pk_mul_f32 v[24:25], v[6:7], v[24:25]
	v_pk_mul_f32 v[26:27], v[8:9], v[26:27]
	global_store_dwordx4 v[28:29], v[24:27], off offset:1024
	s_nop 1
	v_pk_mul_f32 v[24:25], v[52:53], v[0:1] op_sel_hi:[1,0]
	v_pk_mul_f32 v[26:27], v[42:43], v[0:1] op_sel_hi:[1,0]
	v_pk_mul_f32 v[24:25], v[10:11], v[24:25]
	v_pk_mul_f32 v[26:27], v[12:13], v[26:27]
	global_store_dwordx4 v[28:29], v[24:27], off offset:2048
	s_nop 1
	v_pk_mul_f32 v[24:25], v[48:49], v[0:1] op_sel_hi:[1,0]
	v_pk_mul_f32 v[26:27], v[38:39], v[0:1] op_sel_hi:[1,0]
	v_pk_mul_f32 v[24:25], v[14:15], v[24:25]
	v_pk_mul_f32 v[26:27], v[16:17], v[26:27]
	global_store_dwordx4 v[28:29], v[24:27], off offset:3072
	s_cbranch_scc1 .LF_exit
	s_waitcnt vmcnt(8)
	s_branch .LF_copy
.LF_exit:
.LBB0_273:
	s_mov_b64 s[6:7], 0
	v_writelane_b32 v254, s6, 46
	s_nop 1
	v_writelane_b32 v254, s7, 47
